# attention: tile barrier one MFMA earlier (three PV MFMAs issued behind it instead of two)
# speedup vs baseline: 1.0051x; 1.0051x over previous
; __device__ __forceinline__ unsigned cvt_pk_bf16(float lo, float hi) { unsigned r; asm volatile("v_cvt_pk_bf16_f32 %0, %1, %2" : "=v"(r) : "v"(lo), "v"(hi)); return r; }
; __device__ __forceinline__ float fast_exp2(float x) { return __builtin_amdgcn_exp2f(x); }
; #define LGK(n, f) asm volatile("s_waitcnt lgkmcnt(%1)" : "+v"(f) : "n"(n))
; #define ATT_VRD(j) DSR(fr_[(j) & 3], vad[(j) >> 2], ((j) & 3) * 4096)
; __device__ __forceinline__ void attn_phase(int wv, const bf16_t* Q, const bf16_t* Kf, const bf16_t* Vt, const bf16_t* proj, bf16_t* mixed, LAS unsigned char* lds) { LIDS
;     ...
;                     float mx = -1e30f;
; #pragma unroll
;                     for (int kb = 0; kb < 2; ++kb)
; #pragma unroll
;                         for (int j = 0; j < 16; ++j) mx = fmaxf(mx, s[kb][j]);
;                     mx = fmaxf(mx, __shfl_xor(mx, 32));
;                     if (__builtin_amdgcn_ballot_w64(mx > mrun + 8.0f) != 0ull) {
;                         const float mnew = fmaxf(mrun, mx), alpha = fast_exp2(mrun - mnew); mrun = mnew;
;                         lsum *= alpha;
; #pragma unroll
;                         for (int bb = 0; bb < 4; ++bb)
; #pragma unroll
;                             for (int j = 0; j < 16; ++j) o[bb][j] *= alpha;
;                     }
;                     float ps = 0.f;
; #pragma unroll
;                     for (int kb = 0; kb < 2; ++kb)
; #pragma unroll
;                         for (int j = 0; j < 16; ++j) { s[kb][j] = fast_exp2(s[kb][j] - mrun); ps += s[kb][j]; }
;                     lsum += ps;
; #pragma unroll
;                     for (int c = 0; c < 4; ++c) {
;                         const int kb = c >> 1, sx = c & 1;
;                         u32x4 pw;
; #pragma unroll
;                         for (int j = 0; j < 4; ++j) pw[j] = cvt_pk_bf16(s[kb][8 * sx + 2 * j], s[kb][8 * sx + 2 * j + 1]);
;                         const bf16x8 pf = __builtin_bit_cast(bf16x8, pw);
; #pragma unroll
;                         for (int bb = 0; bb < 4; ++bb) {
;                             const int j = c * 4 + bb;
;                             LGK(j < 13 ? 3 : 15 - j, fr_[j & 3]);
;                             o[bb] = __builtin_amdgcn_mfma_f32_32x32x16_bf16(fr_[j & 3], pf, o[bb], 0, 0, 0);
;                             if (j + 4 < 16) ATT_VRD(j + 4);
;                         }
;                     }
.Lp2_nomask2:
	s_waitcnt lgkmcnt(3)
	v_mfma_f32_32x32x16_bf16 v[48:63], v[160:163], v[100:103], v[48:63]
	ds_read_b128 v[160:163], v220 offset:0x6010
	v_max3_f32 v226, v228, v229, v230
	v_max3_f32 v226, v226, v231, v232
	v_max3_f32 v226, v226, v233, v234
	v_max3_f32 v226, v226, v235, v236
	v_max3_f32 v226, v226, v237, v238
	s_waitcnt lgkmcnt(3)
	v_mfma_f32_32x32x16_bf16 v[32:47], v[164:167], v[100:103], v[32:47]
	ds_read_b128 v[164:167], v220 offset:0x7010
	v_max3_f32 v226, v226, v239, v240
	v_max3_f32 v226, v226, v241, v242
	v_max_f32_e32 v226, v226, v243
	v_max3_f32 v227, v178, v179, v180
	v_max3_f32 v227, v227, v181, v182
	s_waitcnt lgkmcnt(3)
	v_mfma_f32_32x32x16_bf16 v[16:31], v[168:171], v[100:103], v[16:31]
	ds_read_b128 v[168:171], v220 offset:0x8010
	v_max3_f32 v227, v227, v183, v184
	v_max3_f32 v227, v227, v185, v186
	v_max3_f32 v227, v227, v187, v188
	v_max3_f32 v227, v227, v189, v190
	v_max3_f32 v227, v227, v191, v192
	s_waitcnt lgkmcnt(3)
	v_mfma_f32_32x32x16_bf16 v[64:79], v[172:175], v[100:103], v[64:79]
	ds_read_b128 v[172:175], v220 offset:0x9010
	v_max_f32_e32 v227, v227, v193
	v_max_f32_e32 v226, v226, v227
	v_mov_b32_e32 v227, v226
	s_nop 1
	v_permlane32_swap_b32_e32 v226, v227
	v_max_f32_e32 v226, v226, v227
	s_waitcnt lgkmcnt(3)
	v_mfma_f32_32x32x16_bf16 v[48:63], v[160:163], v[80:83], v[48:63]
	ds_read_b128 v[160:163], v221 offset:0x6010
	s_waitcnt lgkmcnt(3)
	v_mfma_f32_32x32x16_bf16 v[32:47], v[164:167], v[80:83], v[32:47]
	ds_read_b128 v[164:167], v221 offset:0x7010
	s_waitcnt lgkmcnt(3)
	v_mfma_f32_32x32x16_bf16 v[16:31], v[168:171], v[80:83], v[16:31]
	ds_read_b128 v[168:171], v221 offset:0x8010
	s_waitcnt lgkmcnt(3)
	v_mfma_f32_32x32x16_bf16 v[64:79], v[172:175], v[80:83], v[64:79]
	ds_read_b128 v[172:175], v221 offset:0x9010
	s_waitcnt lgkmcnt(3)
	v_mfma_f32_32x32x16_bf16 v[48:63], v[160:163], v[84:87], v[48:63]
	s_waitcnt lgkmcnt(0)
	s_waitcnt vmcnt(0)
	s_barrier
	ds_read_b128 v[160:163], v207 offset:0x10
	s_waitcnt lgkmcnt(3)
	v_mfma_f32_32x32x16_bf16 v[32:47], v[164:167], v[84:87], v[32:47]
	ds_read_b128 v[164:167], v207 offset:0x3010
	s_waitcnt lgkmcnt(3)
	v_mfma_f32_32x32x16_bf16 v[16:31], v[168:171], v[84:87], v[16:31]
	ds_read_b128 v[168:171], v208 offset:0x10
	s_waitcnt lgkmcnt(3)
	v_mfma_f32_32x32x16_bf16 v[64:79], v[172:175], v[84:87], v[64:79]
	ds_read_b128 v[172:175], v208 offset:0x3010
	v_cmp_gt_f32_e32 vcc, v226, v247
	s_cbranch_vccnz .Lp2_rare0

; __device__ __forceinline__ unsigned cvt_pk_bf16(float lo, float hi) { unsigned r; asm volatile("v_cvt_pk_bf16_f32 %0, %1, %2" : "=v"(r) : "v"(lo), "v"(hi)); return r; }
; __device__ __forceinline__ float fast_exp2(float x) { return __builtin_amdgcn_exp2f(x); }
; #define LGK(n, f) asm volatile("s_waitcnt lgkmcnt(%1)" : "+v"(f) : "n"(n))
; #define ATT_VRD(j) DSR(fr_[(j) & 3], vad[(j) >> 2], ((j) & 3) * 4096)
; __device__ __forceinline__ void attn_phase(int wv, const bf16_t* Q, const bf16_t* Kf, const bf16_t* Vt, const bf16_t* proj, bf16_t* mixed, LAS unsigned char* lds) { LIDS
;     ...
;                     float mx = -1e30f;
; #pragma unroll
;                     for (int kb = 0; kb < 2; ++kb)
; #pragma unroll
;                         for (int j = 0; j < 16; ++j) mx = fmaxf(mx, s[kb][j]);
;                     mx = fmaxf(mx, __shfl_xor(mx, 32));
;                     if (__builtin_amdgcn_ballot_w64(mx > mrun + 8.0f) != 0ull) {
;                         const float mnew = fmaxf(mrun, mx), alpha = fast_exp2(mrun - mnew); mrun = mnew;
;                         lsum *= alpha;
; #pragma unroll
;                         for (int bb = 0; bb < 4; ++bb)
; #pragma unroll
;                             for (int j = 0; j < 16; ++j) o[bb][j] *= alpha;
;                     }
;                     float ps = 0.f;
; #pragma unroll
;                     for (int kb = 0; kb < 2; ++kb)
; #pragma unroll
;                         for (int j = 0; j < 16; ++j) { s[kb][j] = fast_exp2(s[kb][j] - mrun); ps += s[kb][j]; }
;                     lsum += ps;
; #pragma unroll
;                     for (int c = 0; c < 4; ++c) {
;                         const int kb = c >> 1, sx = c & 1;
;                         u32x4 pw;
; #pragma unroll
;                         for (int j = 0; j < 4; ++j) pw[j] = cvt_pk_bf16(s[kb][8 * sx + 2 * j], s[kb][8 * sx + 2 * j + 1]);
;                         const bf16x8 pf = __builtin_bit_cast(bf16x8, pw);
; #pragma unroll
;                         for (int bb = 0; bb < 4; ++bb) {
;                             const int j = c * 4 + bb;
;                             LGK(j < 13 ? 3 : 15 - j, fr_[j & 3]);
;                             o[bb] = __builtin_amdgcn_mfma_f32_32x32x16_bf16(fr_[j & 3], pf, o[bb], 0, 0, 0);
;                             if (j + 4 < 16) ATT_VRD(j + 4);
;                         }
;                     }
.Lp2_nomask8:
	s_waitcnt lgkmcnt(3)
	v_mfma_f32_32x32x16_bf16 v[48:63], v[160:163], v[232:235], v[48:63]
	ds_read_b128 v[160:163], v212 offset:0x8010
	v_max3_f32 v226, v96, v97, v98
	v_max3_f32 v226, v226, v99, v100
	v_max3_f32 v226, v226, v101, v102
	v_max3_f32 v226, v226, v103, v104
	v_max3_f32 v226, v226, v105, v106
	s_waitcnt lgkmcnt(3)
	v_mfma_f32_32x32x16_bf16 v[32:47], v[164:167], v[232:235], v[32:47]
	ds_read_b128 v[164:167], v212 offset:0x9010
	v_max3_f32 v226, v226, v107, v108
	v_max3_f32 v226, v226, v109, v110
	v_max_f32_e32 v226, v226, v111
	v_max3_f32 v227, v80, v81, v82
	v_max3_f32 v227, v227, v83, v84
	s_waitcnt lgkmcnt(3)
	v_mfma_f32_32x32x16_bf16 v[16:31], v[168:171], v[232:235], v[16:31]
	ds_read_b128 v[168:171], v212 offset:0xa010
	v_max3_f32 v227, v227, v85, v86
	v_max3_f32 v227, v227, v87, v88
	v_max3_f32 v227, v227, v89, v90
	v_max3_f32 v227, v227, v91, v92
	v_max3_f32 v227, v227, v93, v94
	s_waitcnt lgkmcnt(3)
	v_mfma_f32_32x32x16_bf16 v[64:79], v[172:175], v[232:235], v[64:79]
	ds_read_b128 v[172:175], v212 offset:0xb010
	v_max_f32_e32 v227, v227, v95
	v_max_f32_e32 v226, v226, v227
	v_mov_b32_e32 v227, v226
	s_nop 1
	v_permlane32_swap_b32_e32 v226, v227
	v_max_f32_e32 v226, v226, v227
	s_waitcnt lgkmcnt(3)
	v_mfma_f32_32x32x16_bf16 v[48:63], v[160:163], v[178:181], v[48:63]
	ds_read_b128 v[160:163], v213 offset:0x8010
	s_waitcnt lgkmcnt(3)
	v_mfma_f32_32x32x16_bf16 v[32:47], v[164:167], v[178:181], v[32:47]
	ds_read_b128 v[164:167], v213 offset:0x9010
	s_waitcnt lgkmcnt(3)
	v_mfma_f32_32x32x16_bf16 v[16:31], v[168:171], v[178:181], v[16:31]
	ds_read_b128 v[168:171], v213 offset:0xa010
	s_waitcnt lgkmcnt(3)
	v_mfma_f32_32x32x16_bf16 v[64:79], v[172:175], v[178:181], v[64:79]
	ds_read_b128 v[172:175], v213 offset:0xb010
	s_waitcnt lgkmcnt(3)
	v_mfma_f32_32x32x16_bf16 v[48:63], v[160:163], v[182:185], v[48:63]
	s_waitcnt lgkmcnt(0)
	s_waitcnt vmcnt(0)
	s_barrier
	ds_read_b128 v[160:163], v207 offset:0xa010
	s_waitcnt lgkmcnt(3)
	v_mfma_f32_32x32x16_bf16 v[32:47], v[164:167], v[182:185], v[32:47]
	ds_read_b128 v[164:167], v207 offset:0xd010
	s_waitcnt lgkmcnt(3)
	v_mfma_f32_32x32x16_bf16 v[16:31], v[168:171], v[182:185], v[16:31]
	ds_read_b128 v[168:171], v208 offset:0xa010
	s_waitcnt lgkmcnt(3)
	v_mfma_f32_32x32x16_bf16 v[64:79], v[172:175], v[182:185], v[64:79]
	ds_read_b128 v[172:175], v208 offset:0xd010
	v_cmp_gt_f32_e32 vcc, v226, v247
	s_cbranch_vccnz .Lp2_rare1
